# prompt attention code shifted by one 4-byte s_nop (instruction placement check), otherwise identical to the previous version
# baseline (speedup 1.0000x reference)
; template<int THRL,bool PART> __device__ __forceinline__ int attn_unit(const bf16*Qb,const bf16*__restrict__ Kh,const bf16*__restrict__ Vh,bf16*Ob,const int NT,const int vlim_in,char*shm,const int s0,const bool primed,const bf16*nKh,const bf16*nVh,bf16*fuseM,const float lam){
;   int tid=threadIdx.x; asm volatile("":"+v"(tid));
;   const int lane=tid&63,r32=lane&31,hi=lane>>5; const int wid=__builtin_amdgcn_readfirstlane(tid>>6);
;   const int vlim=(vlim_in<0)?(wid>>1):vlim_in;
;   const bool act=PART?(wid<2):true;
;   const bf16*Qw=Qb+(long)(wid*QBLK)*KP;
;   const unsigned lds0=(unsigned)(uintptr_t)shm;
;   float*wsf=(float*)(shm+LDS_WS)+wid*64;
;   const bf16*ksrc=Kh+(long)lane*KP+wid*8;
;   const bf16*vsrc=Vh+(long)(16*(wid&3)+(lane>>2))*KP+(wid>>2)*32+(lane&3)*8;
;   const unsigned kdst=lds0+LDS_K+wid*1024, vdst=lds0+LDS_V+wid*1024;
;     ...
;   const int vb0=(int)(lds0+LDS_V)+((lane>>4)&1)*32+(lane&3)*8+(4*hi+((lane&15)>>2))*64;
;   const int s1=(s0==(NSLOT-1)*SLOTB)?0:s0+SLOTB, s2=(s1==(NSLOT-1)*SLOTB)?0:s1+SLOTB;
;   const char*Kbase=shm+LDS_K+s0; bf16x8 kf[8];
;   const lds_cptr shm3=(lds_cptr)shm; const lds_cptr kp0=shm3+LDS_K+hi*1024+r32*16; const lds_cptr vp0=shm3+LDS_V+((lane>>4)&1)*32+(lane&3)*8+(4*hi+((lane&15)>>2))*64;
; __global__ void __launch_bounds__(NWAVES * 64, 2) mk_fwd(Args args) {
;     ...
;         { const float lam = MISC[0];
;         for (int v = vcu; v < 256; v += G) {
;             const int bh = v >> 3, s = v & 7, b = bh >> 2, hd = bh & 3;
;             int ring0 = 0; bool primed = false;
;             for (int i = 0; i < 8; ++i) { const int qb = (i >> 2) ? 15 - s : s, j = (i >> 1) & 1, vh = i & 1;
.LBB0_925:
	s_cmpk_gt_i32 s92, 0xff
	s_waitcnt vmcnt(0) lgkmcnt(0)
	s_barrier
	s_cbranch_scc1 .LBB0_1021
	s_nop 0
	v_mov_b32_e32 v3, 0x1a0000
	global_load_dword v217, v3, s[66:67]
	v_and_b32_e32 v0, 63, v252
	v_and_b32_e32 v1, 31, v252
	v_bfe_u32 v2, v252, 5, 1
	v_lshrrev_b32_e32 v3, 6, v252
	s_nop 0
	v_readfirstlane_b32 s4, v3
	s_and_b32 s5, s4, 3
	s_lshr_b32 s6, s4, 2
	s_mov_b32 s48, 0x41000000
	v_bfe_u32 v219, v1, 1, 3
	v_lshlrev_b32_e32 v220, 7, v1
	v_or_b32_e32 v221, 0, v2
	v_xor_b32_e32 v221, v221, v219
	v_lshl_add_u32 v235, v221, 4, v220
	v_or_b32_e32 v221, 2, v2
	v_xor_b32_e32 v221, v221, v219
	v_lshl_add_u32 v236, v221, 4, v220
	v_or_b32_e32 v221, 4, v2
	v_xor_b32_e32 v221, v221, v219
	v_lshl_add_u32 v237, v221, 4, v220
	v_or_b32_e32 v221, 6, v2
	v_xor_b32_e32 v221, v221, v219
	v_lshl_add_u32 v238, v221, 4, v220
	v_bfe_u32 v218, v0, 4, 1
	v_lshlrev_b32_e32 v229, 5, v218
	v_and_b32_e32 v218, 3, v0
	v_lshl_add_u32 v229, v218, 3, v229
	v_bfe_u32 v218, v0, 2, 2
	v_lshl_add_u32 v218, v2, 2, v218
	v_lshl_add_u32 v229, v218, 6, v229
	s_lshl_b32 s34, s4, 10
	s_add_i32 s34, s34, 0x18000
	v_mov_b32_e32 v230, s34
	v_lshlrev_b32_e32 v240, 2, v1
	v_lshlrev_b32_e32 v241, 4, v2
	v_lshrrev_b32_e32 v218, 3, v0
	s_lshl_b32 s34, s4, 3
	v_add_u32_e32 v218, s34, v218
	v_bfe_u32 v219, v218, 1, 3
	v_and_b32_e32 v220, 7, v0
	v_xor_b32_e32 v219, v219, v220
	v_lshlrev_b32_e32 v231, 10, v218
	v_lshl_add_u32 v231, v219, 4, v231
	v_lshrrev_b32_e32 v218, 2, v0
	v_lshlrev_b32_e32 v232, 10, v218
	v_and_b32_e32 v218, 3, v0
	v_lshl_add_u32 v232, v218, 4, v232
	s_lshl_b32 s34, s5, 14
	s_lshl_b32 s35, s6, 6
	s_add_i32 s34, s34, s35
	v_add_u32_e32 v232, s34, v232
	v_add_u32_e32 v233, 0x80, v232
	v_lshlrev_b32_e32 v234, 10, v1
	v_lshl_add_u32 v234, v2, 4, v234
	v_lshlrev_b32_e32 v239, 4, v0
	s_lshl_b32 s34, s92, 3
	s_add_i32 s34, s34, s4
	s_lshl_b32 s34, s34, 14
	s_add_u32 s52, s66, s34
	s_addc_u32 s53, s67, 0
	s_add_u32 s52, s52, 0x6f00000
	s_addc_u32 s53, s53, 0
	s_waitcnt vmcnt(0)
	v_readfirstlane_b32 s7, v217
	s_mov_b32 s8, s92
